# RMSNorm: norm_g hoisted out of the row loop (kept in registers)
# speedup vs baseline: 1.0082x; 1.0061x over previous
.LBB0_81:
	v_readlane_b32 s4, v252, 0
	v_writelane_b32 v250, s2, 19
	s_and_b64 s[0:1], s[2:3], exec
	v_readlane_b32 s5, v252, 1
	v_readlane_b32 s6, v252, 2
	v_readlane_b32 s7, v252, 3
	v_readlane_b32 s8, v252, 4
	v_readlane_b32 s9, v252, 5
	v_readlane_b32 s10, v252, 6
	v_readlane_b32 s11, v252, 7
	v_writelane_b32 v250, s3, 20
	s_mov_b64 s[22:23], s[10:11]
	v_readlane_b32 s0, v252, 35
	v_readlane_b32 s1, v252, 36
	s_cselect_b32 s1, s1, s23
	s_cselect_b32 s0, s0, s22
	v_writelane_b32 v250, s0, 21
	v_readlane_b32 s5, v252, 40
	v_readlane_b32 s4, v252, 39
	v_writelane_b32 v250, s1, 22
	v_readlane_b32 s0, v252, 29
	s_cselect_b32 s49, s5, s0
	v_readlane_b32 s0, v252, 28
	v_mov_b32_e32 v2, v1
	s_cselect_b32 s48, s4, s0
	v_readlane_b32 s0, v252, 30
	v_ashrrev_i32_e32 v3, 6, v2
	v_readlane_b32 s12, v252, 47
	v_add_u32_e32 v34, s0, v3
	s_movk_i32 s0, 0x4800
	v_readlane_b32 s2, v252, 37
	v_readlane_b32 s13, v252, 48
	s_movk_i32 s12, 0x47ff
	v_cmp_gt_i32_e32 vcc, s0, v34
	v_readlane_b32 s3, v252, 38
	v_readlane_b32 s6, v252, 41
	v_readlane_b32 s7, v252, 42
	v_readlane_b32 s8, v252, 43
	v_readlane_b32 s9, v252, 44
	v_readlane_b32 s10, v252, 45
	v_readlane_b32 s11, v252, 46
	v_readlane_b32 s14, v252, 49
	v_readlane_b32 s15, v252, 50
	s_and_saveexec_b64 s[0:1], vcc
	v_readlane_b32 s2, v252, 62
	v_readlane_b32 s13, v251, 18
	s_cbranch_execz .LBB0_86
	v_readlane_b32 s4, v250, 2
	v_readlane_b32 s5, v250, 3
	s_mul_i32 s42, s4, 0xd800
	s_mov_b32 s8, s4
	s_lshl_b64 s[4:5], s[42:43], 2
	v_readlane_b32 s3, v252, 31
	s_add_u32 s6, s3, s4
	v_readlane_b32 s3, v252, 32
	s_addc_u32 s7, s3, s5
	s_lshl_b32 s42, s8, 11
	v_readlane_b32 s52, v252, 35
	s_lshl_b64 s[4:5], s[42:43], 2
	v_readlane_b32 s60, v252, 43
	v_lshlrev_b32_e32 v2, 2, v2
	v_readlane_b32 s61, v252, 44
	s_add_u32 s4, s60, s4
	v_and_b32_e32 v2, 0xfc, v2
	s_addc_u32 s5, s61, s5
	v_lshlrev_b32_e32 v194, 2, v2
	v_cmp_lt_i32_e32 vcc, v235, v234
	v_or_b32_e32 v10, 0x400, v2
	v_lshl_add_u64 v[36:37], s[4:5], 0, v[194:195]
	v_cndmask_b32_e32 v3, v233, v235, vcc
	v_cmp_lt_i32_e32 vcc, v236, v234
	v_lshlrev_b32_e32 v194, 2, v10
	v_or_b32_e32 v12, 0x500, v2
	v_lshlrev_b32_e32 v67, 2, v3
	v_cndmask_b32_e32 v3, v233, v236, vcc
	v_cmp_lt_i32_e32 vcc, v237, v234
	v_lshl_add_u64 v[38:39], s[4:5], 0, v[194:195]
	v_lshlrev_b32_e32 v194, 2, v12
	v_or_b32_e32 v14, 0x600, v2
	v_lshlrev_b32_e32 v76, 2, v3
	v_cndmask_b32_e32 v3, v233, v237, vcc
	v_cmp_lt_i32_e32 vcc, v238, v234
	v_lshl_add_u64 v[40:41], s[4:5], 0, v[194:195]
	v_lshlrev_b32_e32 v194, 2, v14
	v_or_b32_e32 v16, 0x700, v2
	v_lshlrev_b32_e32 v77, 2, v3
	v_cndmask_b32_e32 v3, v233, v238, vcc
	v_cmp_lt_i32_e32 vcc, v239, v234
	v_lshl_add_u64 v[42:43], s[4:5], 0, v[194:195]
	v_lshlrev_b32_e32 v194, 2, v16
	v_readlane_b32 s64, v252, 47
	v_readlane_b32 s65, v252, 48
	v_readlane_b32 s8, v250, 10
	v_lshlrev_b32_e32 v78, 2, v3
	v_cndmask_b32_e32 v3, v233, v239, vcc
	v_cmp_lt_i32_e32 vcc, v240, v234
	v_lshl_add_u64 v[44:45], s[4:5], 0, v[194:195]
	v_ashrrev_i32_e32 v35, 31, v34
	v_readlane_b32 s4, v250, 21
	v_readlane_b32 s66, v252, 49
	v_readlane_b32 s64, v250, 8
	v_readlane_b32 s14, v251, 52
	v_readlane_b32 s9, v250, 11
	v_lshlrev_b32_e32 v79, 2, v3
	v_cndmask_b32_e32 v3, v233, v240, vcc
	v_or_b32_e32 v4, 0x100, v2
	v_or_b32_e32 v6, 0x200, v2
	v_or_b32_e32 v8, 0x300, v2
	v_lshlrev_b32_e32 v194, 1, v2
	v_lshlrev_b64 v[18:19], 13, v[34:35]
	v_readlane_b32 s5, v250, 22
	v_readlane_b32 s66, v250, 17
	v_readlane_b32 s65, v250, 9
	s_mov_b64 s[22:23], 0x2000
	s_mov_b32 s34, 0x5040100
	v_readlane_b32 s15, v251, 53
	s_mov_b32 s21, s9
	v_lshlrev_b32_e32 v80, 2, v3
	v_lshl_add_u64 v[46:47], s[96:97], 0, v[194:195]
	v_lshl_add_u64 v[48:49], s[4:5], 0, v[18:19]
	s_mov_b64 s[8:9], 0
	v_lshlrev_b32_e32 v50, 2, v2
	v_mov_b32_e32 v51, v195
	v_lshlrev_b32_e32 v52, 2, v4
	v_mov_b32_e32 v53, v195
	v_lshlrev_b32_e32 v54, 2, v6
	v_mov_b32_e32 v55, v195
	v_lshlrev_b32_e32 v56, 2, v8
	v_mov_b32_e32 v57, v195
	v_lshlrev_b32_e32 v58, 2, v10
	v_mov_b32_e32 v59, v195
	v_lshlrev_b32_e32 v60, 2, v12
	v_mov_b32_e32 v61, v195
	v_lshlrev_b32_e32 v62, 2, v14
	v_mov_b32_e32 v63, v195
	v_lshlrev_b32_e32 v64, 2, v16
	v_mov_b32_e32 v65, v195
	v_readlane_b32 s53, v252, 36
	v_readlane_b32 s54, v252, 37
	v_readlane_b32 s55, v252, 38
	v_readlane_b32 s56, v252, 39
	v_readlane_b32 s57, v252, 40
	v_readlane_b32 s58, v252, 41
	v_readlane_b32 s59, v252, 42
	v_readlane_b32 s62, v252, 45
	v_readlane_b32 s63, v252, 46
	v_readlane_b32 s67, v252, 50
	global_load_dwordx4 v[94:97], v[36:37], off
	global_load_dwordx4 v[98:101], v[36:37], off offset:1024
	global_load_dwordx4 v[102:105], v[36:37], off offset:2048
	global_load_dwordx4 v[106:109], v[36:37], off offset:3072
	global_load_dwordx4 v[110:113], v[38:39], off
	global_load_dwordx4 v[114:117], v[38:39], off offset:1024
	global_load_dwordx4 v[118:121], v[38:39], off offset:2048
	global_load_dwordx4 v[122:125], v[38:39], off offset:3072
	s_branch .LBB0_84
.LBB0_83:
	s_or_b64 exec, exec, s[10:11]
	v_lshl_add_u64 v[2:3], v[2:3], 0, v[50:51]
	global_load_dwordx4 v[30:33], v[2:3], off
	global_load_dwordx4 v[26:29], v[2:3], off offset:1024
	global_load_dwordx4 v[22:25], v[2:3], off offset:2048
	global_load_dwordx4 v[18:21], v[2:3], off offset:3072
	v_add_co_u32_e32 v2, vcc, s16, v2
	v_min_i32_e32 v81, 0x4000, v34
	s_nop 0
	v_addc_co_u32_e32 v3, vcc, 0, v3, vcc
	global_load_dwordx4 v[14:17], v[2:3], off
	global_load_dwordx4 v[6:9], v[2:3], off offset:1024
	global_load_dwordx4 v[82:85], v[2:3], off offset:2048
	global_load_dwordx4 v[86:89], v[2:3], off offset:3072
	v_ashrrev_i32_e32 v81, 11, v81
	v_mul_i32_i24_e32 v68, 0x1800, v81
	v_ashrrev_i32_e32 v69, 31, v68
	v_lshl_add_u64 v[68:69], v[68:69], 2, s[6:7]
	v_lshlrev_b64 v[72:73], 12, v[72:73]
	v_lshl_add_u64 v[34:35], v[34:35], 0, s[88:89]
	v_cmp_lt_i32_e32 vcc, s12, v34
	s_or_b64 s[8:9], vcc, s[8:9]
	v_lshl_add_u64 v[48:49], v[48:49], 0, s[14:15]
	v_lshl_add_u64 v[74:75], v[68:69], 0, v[50:51]
	v_lshl_add_u64 v[70:71], v[68:69], 0, s[22:23]
	v_lshl_add_u64 v[90:91], v[70:71], 0, v[50:51]
	v_lshl_add_u64 v[4:5], v[68:69], 0, v[58:59]
	v_lshl_add_u64 v[10:11], v[70:71], 0, v[58:59]
	v_lshl_add_u64 v[92:93], v[46:47], 0, v[72:73]
	global_load_dwordx4 v[126:129], v[74:75], off
	global_load_dwordx4 v[158:161], v[90:91], off
	global_load_dwordx4 v[130:133], v[74:75], off offset:1024
	global_load_dwordx4 v[162:165], v[90:91], off offset:1024
	global_load_dwordx4 v[134:137], v[74:75], off offset:2048
	global_load_dwordx4 v[166:169], v[90:91], off offset:2048
	global_load_dwordx4 v[138:141], v[74:75], off offset:3072
	global_load_dwordx4 v[170:173], v[90:91], off offset:3072
	global_load_dwordx4 v[142:145], v[4:5], off
	global_load_dwordx4 v[174:177], v[10:11], off
	global_load_dwordx4 v[146:149], v[4:5], off offset:1024
	global_load_dwordx4 v[178:181], v[10:11], off offset:1024
	global_load_dwordx4 v[150:153], v[4:5], off offset:2048
	global_load_dwordx4 v[182:185], v[10:11], off offset:2048
	global_load_dwordx4 v[154:157], v[4:5], off offset:3072
	global_load_dwordx4 v[186:189], v[10:11], off offset:3072
	s_waitcnt vmcnt(16)
	v_mul_f32_e32 v4, v31, v31
	v_mul_f32_e32 v5, v27, v27
	v_fmac_f32_e32 v4, v30, v30
	v_fmac_f32_e32 v5, v26, v26
	v_fmac_f32_e32 v4, v32, v32
	v_fmac_f32_e32 v5, v28, v28
	v_fmac_f32_e32 v4, v33, v33
	v_fmac_f32_e32 v5, v29, v29
	v_add_f32_e32 v4, v4, v5
	v_mul_f32_e32 v5, v23, v23
	v_fmac_f32_e32 v5, v22, v22
	v_fmac_f32_e32 v5, v24, v24
	v_fmac_f32_e32 v5, v25, v25
	v_add_f32_e32 v4, v4, v5
	v_mul_f32_e32 v5, v19, v19
	v_fmac_f32_e32 v5, v18, v18
	v_fmac_f32_e32 v5, v20, v20
	v_fmac_f32_e32 v5, v21, v21
	v_mov_b32_e32 v10, v15
	v_mov_b32_e32 v11, v7
	v_add_f32_e32 v12, v4, v5
	v_mov_b32_e32 v4, v14
	v_mov_b32_e32 v5, v6
	v_pk_mul_f32 v[10:11], v[10:11], v[10:11]
	s_nop 0
	v_pk_fma_f32 v[4:5], v[4:5], v[4:5], v[10:11]
	v_mov_b32_e32 v10, v16
	v_mov_b32_e32 v11, v8
	v_pk_fma_f32 v[4:5], v[10:11], v[10:11], v[4:5]
	v_mov_b32_e32 v10, v17
	v_mov_b32_e32 v11, v9
	v_pk_fma_f32 v[4:5], v[10:11], v[10:11], v[4:5]
	s_nop 0
	v_add_f32_e32 v4, v12, v4
	v_add_f32_e32 v66, v4, v5
	v_mov_b32_e32 v74, v83
	v_mov_b32_e32 v75, v87
	v_mov_b32_e32 v70, v82
	v_mov_b32_e32 v71, v86
	v_pk_mul_f32 v[74:75], v[74:75], v[74:75]
	s_nop 0
	v_pk_fma_f32 v[70:71], v[70:71], v[70:71], v[74:75]
	v_mov_b32_e32 v74, v84
	v_mov_b32_e32 v75, v88
	v_pk_fma_f32 v[70:71], v[74:75], v[74:75], v[70:71]
	v_mov_b32_e32 v74, v85
	v_mov_b32_e32 v75, v89
	v_pk_fma_f32 v[70:71], v[74:75], v[74:75], v[70:71]
	s_nop 0
	v_add_f32_e32 v66, v66, v70
	v_add_f32_e32 v66, v66, v71
	ds_bpermute_b32 v70, v67, v66
	s_waitcnt lgkmcnt(0)
	v_add_f32_e32 v66, v66, v70
	ds_bpermute_b32 v70, v76, v66
	s_waitcnt lgkmcnt(0)
	v_add_f32_e32 v66, v66, v70
	ds_bpermute_b32 v70, v77, v66
	s_waitcnt lgkmcnt(0)
	v_add_f32_e32 v66, v66, v70
	ds_bpermute_b32 v70, v78, v66
	s_waitcnt lgkmcnt(0)
	v_add_f32_e32 v66, v66, v70
	ds_bpermute_b32 v70, v79, v66
	s_waitcnt lgkmcnt(0)
	v_add_f32_e32 v66, v66, v70
	ds_bpermute_b32 v70, v80, v66
	s_waitcnt lgkmcnt(0)
	v_add_f32_e32 v66, v66, v70
	v_fmamk_f32 v66, v66, 0x3a000000, v230
	v_cmp_gt_f32_e32 vcc, s70, v66
	v_mul_f32_e32 v70, 0x4b800000, v66
	s_nop 0
	v_cndmask_b32_e32 v66, v66, v70, vcc
	v_rsq_f32_e32 v66, v66
	s_nop 0
	v_mul_f32_e32 v70, 0x45800000, v66
	v_cndmask_b32_e32 v66, v66, v70, vcc
	v_pk_mul_f32 v[30:31], v[30:31], v[66:67] op_sel_hi:[1,0]
	v_pk_mul_f32 v[32:33], v[32:33], v[66:67] op_sel_hi:[1,0]
	v_pk_mul_f32 v[26:27], v[26:27], v[66:67] op_sel_hi:[1,0]
	v_pk_mul_f32 v[28:29], v[28:29], v[66:67] op_sel_hi:[1,0]
	v_pk_mul_f32 v[22:23], v[22:23], v[66:67] op_sel_hi:[1,0]
	v_pk_mul_f32 v[24:25], v[24:25], v[66:67] op_sel_hi:[1,0]
	v_pk_mul_f32 v[18:19], v[18:19], v[66:67] op_sel_hi:[1,0]
	v_pk_mul_f32 v[20:21], v[20:21], v[66:67] op_sel_hi:[1,0]
	v_pk_mul_f32 v[14:15], v[14:15], v[66:67] op_sel_hi:[1,0]
	v_pk_mul_f32 v[16:17], v[16:17], v[66:67] op_sel_hi:[1,0]
	v_pk_mul_f32 v[6:7], v[6:7], v[66:67] op_sel_hi:[1,0]
	v_pk_mul_f32 v[8:9], v[8:9], v[66:67] op_sel_hi:[1,0]
	v_pk_mul_f32 v[82:83], v[82:83], v[66:67] op_sel_hi:[1,0]
	v_pk_mul_f32 v[84:85], v[84:85], v[66:67] op_sel_hi:[1,0]
	v_pk_mul_f32 v[86:87], v[86:87], v[66:67] op_sel_hi:[1,0]
	v_pk_mul_f32 v[88:89], v[88:89], v[66:67] op_sel_hi:[1,0]
	s_waitcnt vmcnt(14)
	v_pk_mul_f32 v[30:31], v[94:95], v[30:31]
	v_pk_mul_f32 v[32:33], v[96:97], v[32:33]
	v_pk_add_f32 v[4:5], v[158:159], 1.0 op_sel_hi:[1,0]
	v_pk_add_f32 v[10:11], v[160:161], 1.0 op_sel_hi:[1,0]
	v_pk_fma_f32 v[30:31], v[4:5], v[30:31], v[126:127]
	v_pk_fma_f32 v[32:33], v[10:11], v[32:33], v[128:129]
	v_cvt_pk_bf16_f32 v12, v30, v31
	v_cvt_pk_bf16_f32 v13, v32, v33
	global_store_dwordx2 v[92:93], v[12:13], off
	s_waitcnt vmcnt(13)
	v_pk_mul_f32 v[26:27], v[98:99], v[26:27]
	v_pk_mul_f32 v[28:29], v[100:101], v[28:29]
	v_pk_add_f32 v[4:5], v[162:163], 1.0 op_sel_hi:[1,0]
	v_pk_add_f32 v[10:11], v[164:165], 1.0 op_sel_hi:[1,0]
	v_pk_fma_f32 v[26:27], v[4:5], v[26:27], v[130:131]
	v_pk_fma_f32 v[28:29], v[10:11], v[28:29], v[132:133]
	v_cvt_pk_bf16_f32 v12, v26, v27
	v_cvt_pk_bf16_f32 v13, v28, v29
	global_store_dwordx2 v[92:93], v[12:13], off offset:512
	s_waitcnt vmcnt(12)
	v_pk_mul_f32 v[22:23], v[102:103], v[22:23]
	v_pk_mul_f32 v[24:25], v[104:105], v[24:25]
	v_pk_add_f32 v[4:5], v[166:167], 1.0 op_sel_hi:[1,0]
	v_pk_add_f32 v[10:11], v[168:169], 1.0 op_sel_hi:[1,0]
	v_pk_fma_f32 v[22:23], v[4:5], v[22:23], v[134:135]
	v_pk_fma_f32 v[24:25], v[10:11], v[24:25], v[136:137]
	v_cvt_pk_bf16_f32 v12, v22, v23
	v_cvt_pk_bf16_f32 v13, v24, v25
	global_store_dwordx2 v[92:93], v[12:13], off offset:1024
	s_waitcnt vmcnt(11)
	v_pk_mul_f32 v[18:19], v[106:107], v[18:19]
	v_pk_mul_f32 v[20:21], v[108:109], v[20:21]
	v_pk_add_f32 v[4:5], v[170:171], 1.0 op_sel_hi:[1,0]
	v_pk_add_f32 v[10:11], v[172:173], 1.0 op_sel_hi:[1,0]
	v_pk_fma_f32 v[18:19], v[4:5], v[18:19], v[138:139]
	v_pk_fma_f32 v[20:21], v[10:11], v[20:21], v[140:141]
	v_cvt_pk_bf16_f32 v12, v18, v19
	v_cvt_pk_bf16_f32 v13, v20, v21
	global_store_dwordx2 v[92:93], v[12:13], off offset:1536
	s_waitcnt vmcnt(10)
	v_pk_mul_f32 v[14:15], v[110:111], v[14:15]
	v_pk_mul_f32 v[16:17], v[112:113], v[16:17]
	v_pk_add_f32 v[4:5], v[174:175], 1.0 op_sel_hi:[1,0]
	v_pk_add_f32 v[10:11], v[176:177], 1.0 op_sel_hi:[1,0]
	v_pk_fma_f32 v[14:15], v[4:5], v[14:15], v[142:143]
	v_pk_fma_f32 v[16:17], v[10:11], v[16:17], v[144:145]
	v_cvt_pk_bf16_f32 v12, v14, v15
	v_cvt_pk_bf16_f32 v13, v16, v17
	global_store_dwordx2 v[92:93], v[12:13], off offset:2048
	s_waitcnt vmcnt(9)
	v_pk_mul_f32 v[6:7], v[114:115], v[6:7]
	v_pk_mul_f32 v[8:9], v[116:117], v[8:9]
	v_pk_add_f32 v[4:5], v[178:179], 1.0 op_sel_hi:[1,0]
	v_pk_add_f32 v[10:11], v[180:181], 1.0 op_sel_hi:[1,0]
	v_pk_fma_f32 v[6:7], v[4:5], v[6:7], v[146:147]
	v_pk_fma_f32 v[8:9], v[10:11], v[8:9], v[148:149]
	v_cvt_pk_bf16_f32 v12, v6, v7
	v_cvt_pk_bf16_f32 v13, v8, v9
	global_store_dwordx2 v[92:93], v[12:13], off offset:2560
	s_waitcnt vmcnt(8)
	v_pk_mul_f32 v[82:83], v[118:119], v[82:83]
	v_pk_mul_f32 v[84:85], v[120:121], v[84:85]
	v_pk_add_f32 v[4:5], v[182:183], 1.0 op_sel_hi:[1,0]
	v_pk_add_f32 v[10:11], v[184:185], 1.0 op_sel_hi:[1,0]
	v_pk_fma_f32 v[82:83], v[4:5], v[82:83], v[150:151]
	v_pk_fma_f32 v[84:85], v[10:11], v[84:85], v[152:153]
	v_cvt_pk_bf16_f32 v12, v82, v83
	v_cvt_pk_bf16_f32 v13, v84, v85
	global_store_dwordx2 v[92:93], v[12:13], off offset:3072
	s_waitcnt vmcnt(7)
	v_pk_mul_f32 v[86:87], v[122:123], v[86:87]
	v_pk_mul_f32 v[88:89], v[124:125], v[88:89]
	v_pk_add_f32 v[4:5], v[186:187], 1.0 op_sel_hi:[1,0]
	v_pk_add_f32 v[10:11], v[188:189], 1.0 op_sel_hi:[1,0]
	v_pk_fma_f32 v[86:87], v[4:5], v[86:87], v[154:155]
	v_pk_fma_f32 v[88:89], v[10:11], v[88:89], v[156:157]
	v_cvt_pk_bf16_f32 v12, v86, v87
	v_cvt_pk_bf16_f32 v13, v88, v89
	global_store_dwordx2 v[92:93], v[12:13], off offset:3584
	s_andn2_b64 exec, exec, s[8:9]
	s_cbranch_execz .LBB0_86
